# GEMM K-loop: in the two-load segments the LDS-DMA loads issue before the 16 ds_reads (more latency budget)
# baseline (speedup 1.0000x reference)
; #define PG8_STAGE(bufoff, gbase, voff) do { _Pragma("unroll") for (int _i = 0; _i < 2; ++_i) \
;         __builtin_amdgcn_global_load_lds((const unsigned*)((const char*)(gbase) + (voff)[_i]), (PG8_LAS unsigned*)(lds + (bufoff) + ldsw + _i * 8192), 16, 0, 0); } while (0)
; #define PG8_LDA(dst, b, h) do { _Pragma("unroll") for (int m = 0; m < 4; ++m) _Pragma("unroll") for (int k = 0; k < 2; ++k) dst[m][k] = *(const PG8_LAS bf16x8*)(lds + PG8_SA(b, h) + aoff + m * 2048 + k * 1024); } while (0)
; #define PG8_LDB(dst, b, h) do { _Pragma("unroll") for (int n = 0; n < 2; ++n) _Pragma("unroll") for (int k = 0; k < 2; ++k) dst[n][k] = *(const PG8_LAS bf16x8*)(lds + PG8_SB(b, h) + boff + n * 2048 + k * 1024); } while (0)
; #define PG8_WAIT_V(n) asm volatile("s_waitcnt vmcnt(" #n ")" ::: "memory")
; #define PG8_WAIT_L(n) asm volatile("s_waitcnt lgkmcnt(" #n ")" ::: "memory")
; #define PG8_BAR __builtin_amdgcn_s_barrier()
; #define PG8_SCHED __builtin_amdgcn_sched_barrier(0)
; template <class Epi, class Sched, bool ALIGN_EPI = false, bool SP2 = false>
; __device__ __forceinline__ void gemm_phase(PG8_LAS unsigned char* lds, const Gemm g, const Sched& S, const Epi& E) {
;     ...
;         const char* nA = has_next ? (const char*)g.A + (size_t)nxt.pm * tstep : cA; const char* nB = has_next ? (const char*)g.Bt + (size_t)nxt.pn * tstep : cB;
;         for (int t = 0; t < nt; t += 2) {
;             const bool last = (t == nt - 2);
;             const char* a1 = cA + (size_t)(t + 1) * kstepB;
;             const char* a2 = last ? nA : cA + (size_t)(t + 2) * kstepB; const char* b2 = last ? nB : cB + (size_t)(t + 2) * kstepB;
;             const char* a3 = a2 + kstepB; const char* b3 = b2 + kstepB;
;             if (last && has_next) S.a_ready(nxt);
;             if constexpr (SP2) {
;             PG8_LDB(B0, 0, 0); PG8_LDB(B1, 0, 1); PG8_SCHED; PG8_LDA(At, 0, 0); PG8_STAGE(PG8_SA(1, 1), a1 + hstepB, voffA);
;             PG8_WAIT_V(8); PG8_WAIT_L(0); PG8_BAR; PG8_MMA(0, 0, At, B0); PG8_MMA(0, 1, At, B1); PG8_BAR; PG8_SCHED;
;             PG8_LDA(At, 0, 1); PG8_STAGE(PG8_SB(0, 0), b2, voffB); PG8_STAGE(PG8_SB(0, 1), b2 + hstepB, voffB); PG8_STAGE(PG8_SA(0, 0), a2, voffA);
;             PG8_WAIT_V(8); PG8_WAIT_L(0); PG8_BAR; PG8_MMA(1, 0, At, B0); PG8_MMA(1, 1, At, B1); PG8_BAR; PG8_SCHED;
.LBB0_193:
	s_add_i32 s84, s38, 2
	s_add_u32 s39, s36, 0x4000
	s_addc_u32 s40, s37, 0
	s_cmp_eq_u32 s31, s38
	s_cselect_b32 s42, s8, s39
	s_cselect_b32 s43, s9, s40
	s_cselect_b32 s40, s62, s78
	s_cselect_b32 s41, s63, s82
	s_add_u32 s38, s42, 0x8000
	s_addc_u32 s39, s43, 0
	s_add_i32 s90, 0, 0x10000
	s_add_i32 s64, 0, 0x14000
	v_lshl_add_u64 v[172:173], s[36:37], 0, v[168:169]
	s_add_i32 m0, s21, 0xc000
	s_nop 0
	global_load_lds_dwordx4 v[172:173], off
	v_lshl_add_u64 v[172:173], s[36:37], 0, v[170:171]
	s_add_i32 m0, s21, 0xe000
	s_nop 0
	global_load_lds_dwordx4 v[172:173], off
	v_add_u32_e32 v140, s90, v174
	v_add_u32_e32 v161, s64, v174
	ds_read_b128 v[128:131], v140
	ds_read_b128 v[132:135], v140 offset:1024
	ds_read_b128 v[136:139], v140 offset:2048
	ds_read_b128 v[140:143], v140 offset:3072
	ds_read_b128 v[144:147], v161
	ds_read_b128 v[148:151], v161 offset:1024
	ds_read_b128 v[178:181], v161 offset:2048
	ds_read_b128 v[182:185], v161 offset:3072
	ds_read_b128 v[186:189], v177
	ds_read_b128 v[190:193], v177 offset:1024
	ds_read_b128 v[194:197], v177 offset:2048
	ds_read_b128 v[198:201], v177 offset:3072
	ds_read_b128 v[202:205], v177 offset:4096
	ds_read_b128 v[206:209], v177 offset:5120
	ds_read_b128 v[210:213], v177 offset:6144
	ds_read_b128 v[214:217], v177 offset:7168
	s_waitcnt vmcnt(8)
	s_waitcnt lgkmcnt(0)
	s_barrier
	s_setprio 1
	s_waitcnt lgkmcnt(0)
	v_mfma_f32_16x16x32_bf16 v[124:127], v[128:131], v[186:189], v[124:127]
	v_mfma_f32_16x16x32_bf16 v[124:127], v[132:135], v[190:193], v[124:127]
	v_mfma_f32_16x16x32_bf16 v[120:123], v[136:139], v[186:189], v[120:123]
	v_mfma_f32_16x16x32_bf16 v[120:123], v[140:143], v[190:193], v[120:123]
	v_mfma_f32_16x16x32_bf16 v[108:111], v[128:131], v[194:197], v[108:111]
	v_mfma_f32_16x16x32_bf16 v[108:111], v[132:135], v[198:201], v[108:111]
	v_mfma_f32_16x16x32_bf16 v[104:107], v[136:139], v[194:197], v[104:107]
	v_mfma_f32_16x16x32_bf16 v[104:107], v[140:143], v[198:201], v[104:107]
	v_mfma_f32_16x16x32_bf16 v[92:95], v[128:131], v[202:205], v[92:95]
	v_mfma_f32_16x16x32_bf16 v[92:95], v[132:135], v[206:209], v[92:95]
	v_mfma_f32_16x16x32_bf16 v[88:91], v[136:139], v[202:205], v[88:91]
	v_mfma_f32_16x16x32_bf16 v[88:91], v[140:143], v[206:209], v[88:91]
	v_mfma_f32_16x16x32_bf16 v[76:79], v[128:131], v[210:213], v[76:79]
	v_mfma_f32_16x16x32_bf16 v[76:79], v[132:135], v[214:217], v[76:79]
	v_mfma_f32_16x16x32_bf16 v[72:75], v[136:139], v[210:213], v[72:75]
	v_mfma_f32_16x16x32_bf16 v[72:75], v[140:143], v[214:217], v[72:75]
	s_setprio 0
	s_setprio 1
	v_mfma_f32_16x16x32_bf16 v[116:119], v[144:147], v[186:189], v[116:119]
	v_mfma_f32_16x16x32_bf16 v[116:119], v[148:151], v[190:193], v[116:119]
	v_mfma_f32_16x16x32_bf16 v[112:115], v[178:181], v[186:189], v[112:115]
	v_mfma_f32_16x16x32_bf16 v[112:115], v[182:185], v[190:193], v[112:115]
	v_mfma_f32_16x16x32_bf16 v[100:103], v[144:147], v[194:197], v[100:103]
	v_mfma_f32_16x16x32_bf16 v[100:103], v[148:151], v[198:201], v[100:103]
	v_mfma_f32_16x16x32_bf16 v[96:99], v[178:181], v[194:197], v[96:99]
	v_mfma_f32_16x16x32_bf16 v[96:99], v[182:185], v[198:201], v[96:99]
	v_mfma_f32_16x16x32_bf16 v[84:87], v[144:147], v[202:205], v[84:87]
	v_mfma_f32_16x16x32_bf16 v[84:87], v[148:151], v[206:209], v[84:87]
	v_mfma_f32_16x16x32_bf16 v[80:83], v[178:181], v[202:205], v[80:83]
	v_mfma_f32_16x16x32_bf16 v[80:83], v[182:185], v[206:209], v[80:83]
	v_mfma_f32_16x16x32_bf16 v[68:71], v[144:147], v[210:213], v[68:71]
	v_mfma_f32_16x16x32_bf16 v[68:71], v[148:151], v[214:217], v[68:71]
	v_mfma_f32_16x16x32_bf16 v[64:67], v[178:181], v[210:213], v[64:67]
	v_mfma_f32_16x16x32_bf16 v[64:67], v[182:185], v[214:217], v[64:67]
	s_setprio 0
	s_barrier
	s_add_i32 s65, s90, s20
	v_lshl_add_u64 v[172:173], s[40:41], 0, v[156:157]
	s_mov_b32 m0, s65
	ds_read_b128 v[186:189], v177 offset:16384
	ds_read_b128 v[190:193], v177 offset:17408
	ds_read_b128 v[194:197], v177 offset:18432
	ds_read_b128 v[198:201], v177 offset:19456
	ds_read_b128 v[202:205], v177 offset:20480
	ds_read_b128 v[206:209], v177 offset:21504
	ds_read_b128 v[210:213], v177 offset:22528
	ds_read_b128 v[214:217], v177 offset:23552
	global_load_lds_dwordx4 v[172:173], off
	s_add_i32 m0, s65, 0x2000
	s_add_u32 vcc_lo, s40, 0x4000
	v_lshl_add_u64 v[172:173], s[40:41], 0, v[152:153]
	s_addc_u32 vcc_hi, s41, 0
	s_add_i32 s64, s64, s20
	global_load_lds_dwordx4 v[172:173], off
	v_lshl_add_u64 v[172:173], vcc, 0, v[156:157]
	s_mov_b32 m0, s64
	s_nop 0
	global_load_lds_dwordx4 v[172:173], off
	v_lshl_add_u64 v[172:173], vcc, 0, v[152:153]
	s_add_i32 m0, s64, 0x2000
	s_nop 0
	global_load_lds_dwordx4 v[172:173], off
	v_lshl_add_u64 v[172:173], s[42:43], 0, v[158:159]
	s_mov_b32 m0, s21
	s_nop 0
	global_load_lds_dwordx4 v[172:173], off
	v_lshl_add_u64 v[172:173], s[42:43], 0, v[154:155]
	s_mov_b32 m0, s22
	s_nop 0
	global_load_lds_dwordx4 v[172:173], off
	s_waitcnt vmcnt(8)
	s_waitcnt lgkmcnt(0)
	s_barrier
; #define PG8_STAGE(bufoff, gbase, voff) do { _Pragma("unroll") for (int _i = 0; _i < 2; ++_i) \
;         __builtin_amdgcn_global_load_lds((const unsigned*)((const char*)(gbase) + (voff)[_i]), (PG8_LAS unsigned*)(lds + (bufoff) + ldsw + _i * 8192), 16, 0, 0); } while (0)
; #define PG8_LDA(dst, b, h) do { _Pragma("unroll") for (int m = 0; m < 4; ++m) _Pragma("unroll") for (int k = 0; k < 2; ++k) dst[m][k] = *(const PG8_LAS bf16x8*)(lds + PG8_SA(b, h) + aoff + m * 2048 + k * 1024); } while (0)
; #define PG8_LDB(dst, b, h) do { _Pragma("unroll") for (int n = 0; n < 2; ++n) _Pragma("unroll") for (int k = 0; k < 2; ++k) dst[n][k] = *(const PG8_LAS bf16x8*)(lds + PG8_SB(b, h) + boff + n * 2048 + k * 1024); } while (0)
; #define PG8_MMA(ai, bj, At, Bt) do { __builtin_amdgcn_s_setprio(1); _Pragma("unroll") for (int m = 0; m < 4; ++m) _Pragma("unroll") for (int n = 0; n < 2; ++n) _Pragma("unroll") for (int k = 0; k < 2; ++k) \
;         acc[ai][bj][m][n] = __builtin_amdgcn_mfma_f32_16x16x32_bf16(Bt[n][k], At[m][k], acc[ai][bj][m][n], 0, 0, 0); __builtin_amdgcn_s_setprio(0); } while (0)
; #define PG8_WAIT_V(n) asm volatile("s_waitcnt vmcnt(" #n ")" ::: "memory")
; #define PG8_WAIT_L(n) asm volatile("s_waitcnt lgkmcnt(" #n ")" ::: "memory")
; #define PG8_BAR __builtin_amdgcn_s_barrier()
; #define PG8_SCHED __builtin_amdgcn_sched_barrier(0)
; template <class Epi, class Sched, bool ALIGN_EPI = false, bool SP2 = false>
; __device__ __forceinline__ void gemm_phase(PG8_LAS unsigned char* lds, const Gemm g, const Sched& S, const Epi& E) {
;     ...
;             PG8_WAIT_V(8); PG8_WAIT_L(0); PG8_BAR; PG8_MMA(1, 0, At, B0); PG8_MMA(1, 1, At, B1); PG8_BAR; PG8_SCHED;
;             PG8_LDB(B0, 1, 0); PG8_LDB(B1, 1, 1); PG8_SCHED; PG8_LDA(At, 1, 0); PG8_STAGE(PG8_SA(0, 1), a2 + hstepB, voffA);
;             PG8_WAIT_V(8); PG8_WAIT_L(0); PG8_BAR; PG8_MMA(0, 0, At, B0); PG8_MMA(0, 1, At, B1); PG8_BAR; PG8_SCHED;
	s_setprio 1
	s_waitcnt lgkmcnt(0)
	v_mfma_f32_16x16x32_bf16 v[60:63], v[128:131], v[186:189], v[60:63]
	v_mfma_f32_16x16x32_bf16 v[60:63], v[132:135], v[190:193], v[60:63]
	v_mfma_f32_16x16x32_bf16 v[56:59], v[136:139], v[186:189], v[56:59]
	v_mfma_f32_16x16x32_bf16 v[56:59], v[140:143], v[190:193], v[56:59]
	v_mfma_f32_16x16x32_bf16 v[44:47], v[128:131], v[194:197], v[44:47]
	v_mfma_f32_16x16x32_bf16 v[44:47], v[132:135], v[198:201], v[44:47]
	v_mfma_f32_16x16x32_bf16 v[40:43], v[136:139], v[194:197], v[40:43]
	v_mfma_f32_16x16x32_bf16 v[40:43], v[140:143], v[198:201], v[40:43]
	v_mfma_f32_16x16x32_bf16 v[28:31], v[128:131], v[202:205], v[28:31]
	v_mfma_f32_16x16x32_bf16 v[28:31], v[132:135], v[206:209], v[28:31]
	v_mfma_f32_16x16x32_bf16 v[24:27], v[136:139], v[202:205], v[24:27]
	v_mfma_f32_16x16x32_bf16 v[24:27], v[140:143], v[206:209], v[24:27]
	v_mfma_f32_16x16x32_bf16 v[12:15], v[128:131], v[210:213], v[12:15]
	v_mfma_f32_16x16x32_bf16 v[12:15], v[132:135], v[214:217], v[12:15]
	v_mfma_f32_16x16x32_bf16 v[8:11], v[136:139], v[210:213], v[8:11]
	v_mfma_f32_16x16x32_bf16 v[8:11], v[140:143], v[214:217], v[8:11]
	s_setprio 0
	s_setprio 1
	v_mfma_f32_16x16x32_bf16 v[52:55], v[144:147], v[186:189], v[52:55]
	v_mfma_f32_16x16x32_bf16 v[52:55], v[148:151], v[190:193], v[52:55]
	v_mfma_f32_16x16x32_bf16 v[48:51], v[178:181], v[186:189], v[48:51]
	v_mfma_f32_16x16x32_bf16 v[48:51], v[182:185], v[190:193], v[48:51]
	v_mfma_f32_16x16x32_bf16 v[36:39], v[144:147], v[194:197], v[36:39]
	v_mfma_f32_16x16x32_bf16 v[36:39], v[148:151], v[198:201], v[36:39]
	v_mfma_f32_16x16x32_bf16 v[32:35], v[178:181], v[194:197], v[32:35]
	v_mfma_f32_16x16x32_bf16 v[32:35], v[182:185], v[198:201], v[32:35]
	v_mfma_f32_16x16x32_bf16 v[20:23], v[144:147], v[202:205], v[20:23]
	v_mfma_f32_16x16x32_bf16 v[20:23], v[148:151], v[206:209], v[20:23]
	v_mfma_f32_16x16x32_bf16 v[16:19], v[178:181], v[202:205], v[16:19]
	v_mfma_f32_16x16x32_bf16 v[16:19], v[182:185], v[206:209], v[16:19]
	v_mfma_f32_16x16x32_bf16 v[4:7], v[144:147], v[210:213], v[4:7]
	v_mfma_f32_16x16x32_bf16 v[4:7], v[148:151], v[214:217], v[4:7]
	v_mfma_f32_16x16x32_bf16 v[0:3], v[178:181], v[210:213], v[0:3]
	v_mfma_f32_16x16x32_bf16 v[0:3], v[182:185], v[214:217], v[0:3]
	s_setprio 0
	s_barrier
	s_add_i32 s64, 0, 0x18000
	s_add_i32 s65, 0, 0x1c000
	s_add_u32 s42, s42, 0x4000
	s_addc_u32 s43, s43, 0
	s_mov_b32 m0, s23
	v_lshl_add_u64 v[172:173], s[42:43], 0, v[158:159]
	global_load_lds_dwordx4 v[172:173], off
	v_lshl_add_u64 v[172:173], s[42:43], 0, v[154:155]
	s_mov_b32 m0, s24
	s_nop 0
	global_load_lds_dwordx4 v[172:173], off
	v_add_u32_e32 v140, s64, v174
	v_add_u32_e32 v161, s65, v174
	ds_read_b128 v[128:131], v140
	ds_read_b128 v[132:135], v140 offset:1024
	ds_read_b128 v[136:139], v140 offset:2048
	ds_read_b128 v[140:143], v140 offset:3072
	ds_read_b128 v[144:147], v161
	ds_read_b128 v[148:151], v161 offset:1024
	ds_read_b128 v[178:181], v161 offset:2048
	ds_read_b128 v[182:185], v161 offset:3072
	ds_read_b128 v[186:189], v177 offset:32768
	ds_read_b128 v[190:193], v177 offset:33792
	ds_read_b128 v[194:197], v177 offset:34816
	ds_read_b128 v[198:201], v177 offset:35840
	ds_read_b128 v[202:205], v177 offset:36864
	ds_read_b128 v[206:209], v177 offset:37888
	ds_read_b128 v[210:213], v177 offset:38912
	ds_read_b128 v[214:217], v177 offset:39936
	s_waitcnt vmcnt(8)
	s_waitcnt lgkmcnt(0)
	s_barrier
	s_setprio 1
	s_waitcnt lgkmcnt(0)
	v_mfma_f32_16x16x32_bf16 v[124:127], v[128:131], v[186:189], v[124:127]
	v_mfma_f32_16x16x32_bf16 v[124:127], v[132:135], v[190:193], v[124:127]
	v_mfma_f32_16x16x32_bf16 v[120:123], v[136:139], v[186:189], v[120:123]
	v_mfma_f32_16x16x32_bf16 v[120:123], v[140:143], v[190:193], v[120:123]
	v_mfma_f32_16x16x32_bf16 v[108:111], v[128:131], v[194:197], v[108:111]
	v_mfma_f32_16x16x32_bf16 v[108:111], v[132:135], v[198:201], v[108:111]
	v_mfma_f32_16x16x32_bf16 v[104:107], v[136:139], v[194:197], v[104:107]
	v_mfma_f32_16x16x32_bf16 v[104:107], v[140:143], v[198:201], v[104:107]
	v_mfma_f32_16x16x32_bf16 v[92:95], v[128:131], v[202:205], v[92:95]
	v_mfma_f32_16x16x32_bf16 v[92:95], v[132:135], v[206:209], v[92:95]
	v_mfma_f32_16x16x32_bf16 v[88:91], v[136:139], v[202:205], v[88:91]
	v_mfma_f32_16x16x32_bf16 v[88:91], v[140:143], v[206:209], v[88:91]
	v_mfma_f32_16x16x32_bf16 v[76:79], v[128:131], v[210:213], v[76:79]
	v_mfma_f32_16x16x32_bf16 v[76:79], v[132:135], v[214:217], v[76:79]
	v_mfma_f32_16x16x32_bf16 v[72:75], v[136:139], v[210:213], v[72:75]
	v_mfma_f32_16x16x32_bf16 v[72:75], v[140:143], v[214:217], v[72:75]
	s_setprio 0
	s_setprio 1
	v_mfma_f32_16x16x32_bf16 v[116:119], v[144:147], v[186:189], v[116:119]
	v_mfma_f32_16x16x32_bf16 v[116:119], v[148:151], v[190:193], v[116:119]
	v_mfma_f32_16x16x32_bf16 v[112:115], v[178:181], v[186:189], v[112:115]
	v_mfma_f32_16x16x32_bf16 v[112:115], v[182:185], v[190:193], v[112:115]
	v_mfma_f32_16x16x32_bf16 v[100:103], v[144:147], v[194:197], v[100:103]
	v_mfma_f32_16x16x32_bf16 v[100:103], v[148:151], v[198:201], v[100:103]
	v_mfma_f32_16x16x32_bf16 v[96:99], v[178:181], v[194:197], v[96:99]
	v_mfma_f32_16x16x32_bf16 v[96:99], v[182:185], v[198:201], v[96:99]
	v_mfma_f32_16x16x32_bf16 v[84:87], v[144:147], v[202:205], v[84:87]
	v_mfma_f32_16x16x32_bf16 v[84:87], v[148:151], v[206:209], v[84:87]
	v_mfma_f32_16x16x32_bf16 v[80:83], v[178:181], v[202:205], v[80:83]
	v_mfma_f32_16x16x32_bf16 v[80:83], v[182:185], v[206:209], v[80:83]
	v_mfma_f32_16x16x32_bf16 v[68:71], v[144:147], v[210:213], v[68:71]
	v_mfma_f32_16x16x32_bf16 v[68:71], v[148:151], v[214:217], v[68:71]
	v_mfma_f32_16x16x32_bf16 v[64:67], v[178:181], v[210:213], v[64:67]
	v_mfma_f32_16x16x32_bf16 v[64:67], v[182:185], v[214:217], v[64:67]
	s_setprio 0
	s_barrier
; #define PG8_STAGE(bufoff, gbase, voff) do { _Pragma("unroll") for (int _i = 0; _i < 2; ++_i) \
;         __builtin_amdgcn_global_load_lds((const unsigned*)((const char*)(gbase) + (voff)[_i]), (PG8_LAS unsigned*)(lds + (bufoff) + ldsw + _i * 8192), 16, 0, 0); } while (0)
; #define PG8_LDA(dst, b, h) do { _Pragma("unroll") for (int m = 0; m < 4; ++m) _Pragma("unroll") for (int k = 0; k < 2; ++k) dst[m][k] = *(const PG8_LAS bf16x8*)(lds + PG8_SA(b, h) + aoff + m * 2048 + k * 1024); } while (0)
; #define PG8_MMA(ai, bj, At, Bt) do { __builtin_amdgcn_s_setprio(1); _Pragma("unroll") for (int m = 0; m < 4; ++m) _Pragma("unroll") for (int n = 0; n < 2; ++n) _Pragma("unroll") for (int k = 0; k < 2; ++k) \
;         acc[ai][bj][m][n] = __builtin_amdgcn_mfma_f32_16x16x32_bf16(Bt[n][k], At[m][k], acc[ai][bj][m][n], 0, 0, 0); __builtin_amdgcn_s_setprio(0); } while (0)
; #define PG8_WAIT_V(n) asm volatile("s_waitcnt vmcnt(" #n ")" ::: "memory")
; #define PG8_WAIT_L(n) asm volatile("s_waitcnt lgkmcnt(" #n ")" ::: "memory")
; #define PG8_BAR __builtin_amdgcn_s_barrier()
; #define PG8_SCHED __builtin_amdgcn_sched_barrier(0)
; template <class Epi, class Sched, bool ALIGN_EPI = false, bool SP2 = false>
; __device__ __forceinline__ void gemm_phase(PG8_LAS unsigned char* lds, const Gemm g, const Sched& S, const Epi& E) {
;     ...
;             PG8_LDA(At, 1, 1); PG8_STAGE(PG8_SB(1, 0), b3, voffB); PG8_STAGE(PG8_SB(1, 1), b3 + hstepB, voffB); PG8_STAGE(PG8_SA(1, 0), a3, voffA);
;             PG8_WAIT_V(8); PG8_WAIT_L(0); PG8_BAR; PG8_MMA(1, 0, At, B0); PG8_MMA(1, 1, At, B1); PG8_BAR; PG8_SCHED;
	s_add_u32 s42, s40, 0x8000
	s_addc_u32 s43, s41, 0
	s_add_i32 s64, s64, s20
	v_lshl_add_u64 v[172:173], s[42:43], 0, v[156:157]
	s_mov_b32 m0, s64
	ds_read_b128 v[186:189], v177 offset:49152
	ds_read_b128 v[190:193], v177 offset:50176
	ds_read_b128 v[194:197], v177 offset:51200
	ds_read_b128 v[198:201], v177 offset:52224
	ds_read_b128 v[202:205], v177 offset:53248
	ds_read_b128 v[206:209], v177 offset:54272
	ds_read_b128 v[210:213], v177 offset:55296
	ds_read_b128 v[214:217], v177 offset:56320
	global_load_lds_dwordx4 v[172:173], off
	s_add_i32 m0, s64, 0x2000
	s_add_u32 s40, s40, 0xc000
	v_lshl_add_u64 v[172:173], s[42:43], 0, v[152:153]
	s_addc_u32 s41, s41, 0
	s_add_i32 s42, s65, s20
	global_load_lds_dwordx4 v[172:173], off
	v_lshl_add_u64 v[172:173], s[40:41], 0, v[156:157]
	s_mov_b32 m0, s42
	s_nop 0
	global_load_lds_dwordx4 v[172:173], off
	v_lshl_add_u64 v[172:173], s[40:41], 0, v[152:153]
	s_add_i32 m0, s42, 0x2000
	s_nop 0
	global_load_lds_dwordx4 v[172:173], off
	v_lshl_add_u64 v[172:173], s[38:39], 0, v[158:159]
	s_mov_b32 m0, s29
	s_nop 0
	global_load_lds_dwordx4 v[172:173], off
	v_lshl_add_u64 v[172:173], s[38:39], 0, v[154:155]
	s_mov_b32 m0, s30
	s_nop 0
	global_load_lds_dwordx4 v[172:173], off
	s_waitcnt vmcnt(8)
	s_waitcnt lgkmcnt(0)
	s_barrier
	s_setprio 1
	s_waitcnt lgkmcnt(0)
	v_mfma_f32_16x16x32_bf16 v[60:63], v[128:131], v[186:189], v[60:63]
	v_mfma_f32_16x16x32_bf16 v[60:63], v[132:135], v[190:193], v[60:63]
	v_mfma_f32_16x16x32_bf16 v[56:59], v[136:139], v[186:189], v[56:59]
	v_mfma_f32_16x16x32_bf16 v[56:59], v[140:143], v[190:193], v[56:59]
	v_mfma_f32_16x16x32_bf16 v[44:47], v[128:131], v[194:197], v[44:47]
	v_mfma_f32_16x16x32_bf16 v[44:47], v[132:135], v[198:201], v[44:47]
	v_mfma_f32_16x16x32_bf16 v[40:43], v[136:139], v[194:197], v[40:43]
	v_mfma_f32_16x16x32_bf16 v[40:43], v[140:143], v[198:201], v[40:43]
	v_mfma_f32_16x16x32_bf16 v[28:31], v[128:131], v[202:205], v[28:31]
	v_mfma_f32_16x16x32_bf16 v[28:31], v[132:135], v[206:209], v[28:31]
	v_mfma_f32_16x16x32_bf16 v[24:27], v[136:139], v[202:205], v[24:27]
	v_mfma_f32_16x16x32_bf16 v[24:27], v[140:143], v[206:209], v[24:27]
	v_mfma_f32_16x16x32_bf16 v[12:15], v[128:131], v[210:213], v[12:15]
	v_mfma_f32_16x16x32_bf16 v[12:15], v[132:135], v[214:217], v[12:15]
	v_mfma_f32_16x16x32_bf16 v[8:11], v[136:139], v[210:213], v[8:11]
	v_mfma_f32_16x16x32_bf16 v[8:11], v[140:143], v[214:217], v[8:11]
	s_setprio 0
	s_setprio 1
	v_mfma_f32_16x16x32_bf16 v[52:55], v[144:147], v[186:189], v[52:55]
	v_mfma_f32_16x16x32_bf16 v[52:55], v[148:151], v[190:193], v[52:55]
	v_mfma_f32_16x16x32_bf16 v[48:51], v[178:181], v[186:189], v[48:51]
	v_mfma_f32_16x16x32_bf16 v[48:51], v[182:185], v[190:193], v[48:51]
	v_mfma_f32_16x16x32_bf16 v[36:39], v[144:147], v[194:197], v[36:39]
	v_mfma_f32_16x16x32_bf16 v[36:39], v[148:151], v[198:201], v[36:39]
	v_mfma_f32_16x16x32_bf16 v[32:35], v[178:181], v[194:197], v[32:35]
	v_mfma_f32_16x16x32_bf16 v[32:35], v[182:185], v[198:201], v[32:35]
	v_mfma_f32_16x16x32_bf16 v[20:23], v[144:147], v[202:205], v[20:23]
	v_mfma_f32_16x16x32_bf16 v[20:23], v[148:151], v[206:209], v[20:23]
	v_mfma_f32_16x16x32_bf16 v[16:19], v[178:181], v[202:205], v[16:19]
	v_mfma_f32_16x16x32_bf16 v[16:19], v[182:185], v[206:209], v[16:19]
	v_mfma_f32_16x16x32_bf16 v[4:7], v[144:147], v[210:213], v[4:7]
	v_mfma_f32_16x16x32_bf16 v[4:7], v[148:151], v[214:217], v[4:7]
	v_mfma_f32_16x16x32_bf16 v[0:3], v[178:181], v[210:213], v[0:3]
	v_mfma_f32_16x16x32_bf16 v[0:3], v[182:185], v[214:217], v[0:3]
	s_setprio 0
	s_barrier
	s_add_u32 s36, s36, 0x10000
	s_addc_u32 s37, s37, 0
	s_add_u32 s78, s78, 0x10000
	s_addc_u32 s82, s82, 0
	s_cmp_ge_u32 s84, s26
	s_mov_b32 s38, s84
	s_cbranch_scc0 .LBB0_193
	s_and_b64 vcc, exec, s[60:61]
	s_cbranch_vccz .LBB0_196
	s_barrier

; #define PG8_STAGE(bufoff, gbase, voff) do { _Pragma("unroll") for (int _i = 0; _i < 2; ++_i) \
;         __builtin_amdgcn_global_load_lds((const unsigned*)((const char*)(gbase) + (voff)[_i]), (PG8_LAS unsigned*)(lds + (bufoff) + ldsw + _i * 8192), 16, 0, 0); } while (0)
; #define PG8_LDA(dst, b, h) do { _Pragma("unroll") for (int m = 0; m < 4; ++m) _Pragma("unroll") for (int k = 0; k < 2; ++k) dst[m][k] = *(const PG8_LAS bf16x8*)(lds + PG8_SA(b, h) + aoff + m * 2048 + k * 1024); } while (0)
; #define PG8_LDB(dst, b, h) do { _Pragma("unroll") for (int n = 0; n < 2; ++n) _Pragma("unroll") for (int k = 0; k < 2; ++k) dst[n][k] = *(const PG8_LAS bf16x8*)(lds + PG8_SB(b, h) + boff + n * 2048 + k * 1024); } while (0)
; #define PG8_MMA(ai, bj, At, Bt) do { __builtin_amdgcn_s_setprio(1); _Pragma("unroll") for (int m = 0; m < 4; ++m) _Pragma("unroll") for (int n = 0; n < 2; ++n) _Pragma("unroll") for (int k = 0; k < 2; ++k) \
;         acc[ai][bj][m][n] = __builtin_amdgcn_mfma_f32_16x16x32_bf16(Bt[n][k], At[m][k], acc[ai][bj][m][n], 0, 0, 0); __builtin_amdgcn_s_setprio(0); } while (0)
; #define PG8_WAIT_V(n) asm volatile("s_waitcnt vmcnt(" #n ")" ::: "memory")
; #define PG8_WAIT_L(n) asm volatile("s_waitcnt lgkmcnt(" #n ")" ::: "memory")
; template <class Epi, class Sched, bool ALIGN_EPI = false, bool SP2 = false>
; __device__ __forceinline__ void gemm_phase(PG8_LAS unsigned char* lds, const Gemm g, const Sched& S, const Epi& E) {
;     ...
;             const bool last = (t == nt - 2);
;             const char* a1 = cA + (size_t)(t + 1) * kstepB;
;             const char* a2 = last ? nA : cA + (size_t)(t + 2) * kstepB; const char* b2 = last ? nB : cB + (size_t)(t + 2) * kstepB;
;             const char* a3 = a2 + kstepB; const char* b3 = b2 + kstepB;
;             if (last && has_next) S.a_ready(nxt);
;             if constexpr (SP2) {
;             PG8_LDB(B0, 0, 0); PG8_LDB(B1, 0, 1); PG8_SCHED; PG8_LDA(At, 0, 0); PG8_STAGE(PG8_SA(1, 1), a1 + hstepB, voffA);
;             PG8_WAIT_V(8); PG8_WAIT_L(0); PG8_BAR; PG8_MMA(0, 0, At, B0); PG8_MMA(0, 1, At, B1); PG8_BAR; PG8_SCHED;
;             PG8_LDA(At, 0, 1); PG8_STAGE(PG8_SB(0, 0), b2, voffB); PG8_STAGE(PG8_SB(0, 1), b2 + hstepB, voffB); PG8_STAGE(PG8_SA(0, 0), a2, voffA);
;             PG8_WAIT_V(8); PG8_WAIT_L(0); PG8_BAR; PG8_MMA(1, 0, At, B0); PG8_MMA(1, 1, At, B1); PG8_BAR; PG8_SCHED;
.LBB0_232:
	s_add_u32 s31, s36, 0x4000
	s_addc_u32 s38, s37, 0
	s_cmp_eq_u32 s30, 28
	s_cselect_b32 s42, s26, s31
	s_cselect_b32 s43, s13, s38
	s_cselect_b32 s40, s27, s28
	s_cselect_b32 s41, s11, s29
	s_add_u32 s38, s42, 0x8000
	s_addc_u32 s39, s43, 0
	s_add_i32 s31, 0, 0x10000
	s_add_i32 s60, 0, 0x14000
	v_lshl_add_u64 v[212:213], s[36:37], 0, v[144:145]
	s_add_i32 m0, s17, 0xc000
	s_nop 0
	global_load_lds_dwordx4 v[212:213], off
	v_lshl_add_u64 v[212:213], s[36:37], 0, v[146:147]
	s_add_i32 m0, s17, 0xe000
	s_nop 0
	global_load_lds_dwordx4 v[212:213], off
	v_add_u32_e32 v152, s31, v169
	v_add_u32_e32 v175, s60, v169
	ds_read_b128 v[128:131], v152
	ds_read_b128 v[132:135], v152 offset:1024
	ds_read_b128 v[148:151], v152 offset:2048
	ds_read_b128 v[152:155], v152 offset:3072
	ds_read_b128 v[156:159], v175
	ds_read_b128 v[160:163], v175 offset:1024
	ds_read_b128 v[164:167], v175 offset:2048
	ds_read_b128 v[176:179], v175 offset:3072
	ds_read_b128 v[180:183], v174
	ds_read_b128 v[184:187], v174 offset:1024
	ds_read_b128 v[188:191], v174 offset:2048
	ds_read_b128 v[192:195], v174 offset:3072
	ds_read_b128 v[196:199], v174 offset:4096
	ds_read_b128 v[200:203], v174 offset:5120
	ds_read_b128 v[204:207], v174 offset:6144
	ds_read_b128 v[208:211], v174 offset:7168
	s_waitcnt vmcnt(8)
	s_waitcnt lgkmcnt(0)
	s_barrier
	s_setprio 1
	s_waitcnt lgkmcnt(0)
	v_mfma_f32_16x16x32_bf16 v[124:127], v[128:131], v[180:183], v[124:127]
	v_mfma_f32_16x16x32_bf16 v[124:127], v[132:135], v[184:187], v[124:127]
	v_mfma_f32_16x16x32_bf16 v[120:123], v[148:151], v[180:183], v[120:123]
	v_mfma_f32_16x16x32_bf16 v[120:123], v[152:155], v[184:187], v[120:123]
	v_mfma_f32_16x16x32_bf16 v[108:111], v[128:131], v[188:191], v[108:111]
	v_mfma_f32_16x16x32_bf16 v[108:111], v[132:135], v[192:195], v[108:111]
	v_mfma_f32_16x16x32_bf16 v[104:107], v[148:151], v[188:191], v[104:107]
	v_mfma_f32_16x16x32_bf16 v[104:107], v[152:155], v[192:195], v[104:107]
	v_mfma_f32_16x16x32_bf16 v[92:95], v[128:131], v[196:199], v[92:95]
	v_mfma_f32_16x16x32_bf16 v[92:95], v[132:135], v[200:203], v[92:95]
	v_mfma_f32_16x16x32_bf16 v[88:91], v[148:151], v[196:199], v[88:91]
	v_mfma_f32_16x16x32_bf16 v[88:91], v[152:155], v[200:203], v[88:91]
	v_mfma_f32_16x16x32_bf16 v[76:79], v[128:131], v[204:207], v[76:79]
	v_mfma_f32_16x16x32_bf16 v[76:79], v[132:135], v[208:211], v[76:79]
	v_mfma_f32_16x16x32_bf16 v[72:75], v[148:151], v[204:207], v[72:75]
	v_mfma_f32_16x16x32_bf16 v[72:75], v[152:155], v[208:211], v[72:75]
	s_setprio 0
	s_setprio 1
	v_mfma_f32_16x16x32_bf16 v[116:119], v[156:159], v[180:183], v[116:119]
	v_mfma_f32_16x16x32_bf16 v[116:119], v[160:163], v[184:187], v[116:119]
	v_mfma_f32_16x16x32_bf16 v[112:115], v[164:167], v[180:183], v[112:115]
	v_mfma_f32_16x16x32_bf16 v[112:115], v[176:179], v[184:187], v[112:115]
	v_mfma_f32_16x16x32_bf16 v[100:103], v[156:159], v[188:191], v[100:103]
	v_mfma_f32_16x16x32_bf16 v[100:103], v[160:163], v[192:195], v[100:103]
	v_mfma_f32_16x16x32_bf16 v[96:99], v[164:167], v[188:191], v[96:99]
	v_mfma_f32_16x16x32_bf16 v[96:99], v[176:179], v[192:195], v[96:99]
	v_mfma_f32_16x16x32_bf16 v[84:87], v[156:159], v[196:199], v[84:87]
	v_mfma_f32_16x16x32_bf16 v[84:87], v[160:163], v[200:203], v[84:87]
	v_mfma_f32_16x16x32_bf16 v[80:83], v[164:167], v[196:199], v[80:83]
	v_mfma_f32_16x16x32_bf16 v[80:83], v[176:179], v[200:203], v[80:83]
	v_mfma_f32_16x16x32_bf16 v[68:71], v[156:159], v[204:207], v[68:71]
	v_mfma_f32_16x16x32_bf16 v[68:71], v[160:163], v[208:211], v[68:71]
	v_mfma_f32_16x16x32_bf16 v[64:67], v[164:167], v[204:207], v[64:67]
	v_mfma_f32_16x16x32_bf16 v[64:67], v[176:179], v[208:211], v[64:67]
	s_setprio 0
	s_barrier
	s_add_i32 s31, s31, s14
	v_lshl_add_u64 v[212:213], s[40:41], 0, v[220:221]
	s_mov_b32 m0, s31
	ds_read_b128 v[180:183], v174 offset:16384
	ds_read_b128 v[184:187], v174 offset:17408
	ds_read_b128 v[188:191], v174 offset:18432
	ds_read_b128 v[192:195], v174 offset:19456
	ds_read_b128 v[196:199], v174 offset:20480
	ds_read_b128 v[200:203], v174 offset:21504
	ds_read_b128 v[204:207], v174 offset:22528
	ds_read_b128 v[208:211], v174 offset:23552
	global_load_lds_dwordx4 v[212:213], off
	s_add_i32 m0, s31, 0x2000
	s_add_u32 s44, s40, 0x4000
	v_lshl_add_u64 v[212:213], s[40:41], 0, v[136:137]
	s_addc_u32 s45, s41, 0
	s_add_i32 s31, s60, s14
	global_load_lds_dwordx4 v[212:213], off
	v_lshl_add_u64 v[212:213], s[44:45], 0, v[220:221]
	s_mov_b32 m0, s31
	s_nop 0
	global_load_lds_dwordx4 v[212:213], off
	v_lshl_add_u64 v[212:213], s[44:45], 0, v[136:137]
	s_add_i32 m0, s31, 0x2000
	s_nop 0
	global_load_lds_dwordx4 v[212:213], off
	v_lshl_add_u64 v[212:213], s[42:43], 0, v[140:141]
	s_mov_b32 m0, s17
	s_nop 0
	global_load_lds_dwordx4 v[212:213], off
	v_lshl_add_u64 v[212:213], s[42:43], 0, v[138:139]
	s_mov_b32 m0, s18
	s_nop 0
	global_load_lds_dwordx4 v[212:213], off
	s_waitcnt vmcnt(8)
	s_waitcnt lgkmcnt(0)
	s_barrier
; #define PG8_STAGE(bufoff, gbase, voff) do { _Pragma("unroll") for (int _i = 0; _i < 2; ++_i) \
;         __builtin_amdgcn_global_load_lds((const unsigned*)((const char*)(gbase) + (voff)[_i]), (PG8_LAS unsigned*)(lds + (bufoff) + ldsw + _i * 8192), 16, 0, 0); } while (0)
; #define PG8_LDA(dst, b, h) do { _Pragma("unroll") for (int m = 0; m < 4; ++m) _Pragma("unroll") for (int k = 0; k < 2; ++k) dst[m][k] = *(const PG8_LAS bf16x8*)(lds + PG8_SA(b, h) + aoff + m * 2048 + k * 1024); } while (0)
; #define PG8_LDB(dst, b, h) do { _Pragma("unroll") for (int n = 0; n < 2; ++n) _Pragma("unroll") for (int k = 0; k < 2; ++k) dst[n][k] = *(const PG8_LAS bf16x8*)(lds + PG8_SB(b, h) + boff + n * 2048 + k * 1024); } while (0)
; #define PG8_MMA(ai, bj, At, Bt) do { __builtin_amdgcn_s_setprio(1); _Pragma("unroll") for (int m = 0; m < 4; ++m) _Pragma("unroll") for (int n = 0; n < 2; ++n) _Pragma("unroll") for (int k = 0; k < 2; ++k) \
;         acc[ai][bj][m][n] = __builtin_amdgcn_mfma_f32_16x16x32_bf16(Bt[n][k], At[m][k], acc[ai][bj][m][n], 0, 0, 0); __builtin_amdgcn_s_setprio(0); } while (0)
; #define PG8_WAIT_V(n) asm volatile("s_waitcnt vmcnt(" #n ")" ::: "memory")
; #define PG8_WAIT_L(n) asm volatile("s_waitcnt lgkmcnt(" #n ")" ::: "memory")
; #define PG8_BAR __builtin_amdgcn_s_barrier()
; #define PG8_SCHED __builtin_amdgcn_sched_barrier(0)
; template <class Epi, class Sched, bool ALIGN_EPI = false, bool SP2 = false>
; __device__ __forceinline__ void gemm_phase(PG8_LAS unsigned char* lds, const Gemm g, const Sched& S, const Epi& E) {
;     ...
;             PG8_WAIT_V(8); PG8_WAIT_L(0); PG8_BAR; PG8_MMA(1, 0, At, B0); PG8_MMA(1, 1, At, B1); PG8_BAR; PG8_SCHED;
;             PG8_LDB(B0, 1, 0); PG8_LDB(B1, 1, 1); PG8_SCHED; PG8_LDA(At, 1, 0); PG8_STAGE(PG8_SA(0, 1), a2 + hstepB, voffA);
;             PG8_WAIT_V(8); PG8_WAIT_L(0); PG8_BAR; PG8_MMA(0, 0, At, B0); PG8_MMA(0, 1, At, B1); PG8_BAR; PG8_SCHED;
	s_setprio 1
	s_waitcnt lgkmcnt(0)
	v_mfma_f32_16x16x32_bf16 v[60:63], v[128:131], v[180:183], v[60:63]
	v_mfma_f32_16x16x32_bf16 v[60:63], v[132:135], v[184:187], v[60:63]
	v_mfma_f32_16x16x32_bf16 v[56:59], v[148:151], v[180:183], v[56:59]
	v_mfma_f32_16x16x32_bf16 v[56:59], v[152:155], v[184:187], v[56:59]
	v_mfma_f32_16x16x32_bf16 v[48:51], v[128:131], v[188:191], v[48:51]
	v_mfma_f32_16x16x32_bf16 v[48:51], v[132:135], v[192:195], v[48:51]
	v_mfma_f32_16x16x32_bf16 v[40:43], v[148:151], v[188:191], v[40:43]
	v_mfma_f32_16x16x32_bf16 v[40:43], v[152:155], v[192:195], v[40:43]
	v_mfma_f32_16x16x32_bf16 v[32:35], v[128:131], v[196:199], v[32:35]
	v_mfma_f32_16x16x32_bf16 v[32:35], v[132:135], v[200:203], v[32:35]
	v_mfma_f32_16x16x32_bf16 v[24:27], v[148:151], v[196:199], v[24:27]
	v_mfma_f32_16x16x32_bf16 v[24:27], v[152:155], v[200:203], v[24:27]
	v_mfma_f32_16x16x32_bf16 v[16:19], v[128:131], v[204:207], v[16:19]
	v_mfma_f32_16x16x32_bf16 v[16:19], v[132:135], v[208:211], v[16:19]
	v_mfma_f32_16x16x32_bf16 v[8:11], v[148:151], v[204:207], v[8:11]
	v_mfma_f32_16x16x32_bf16 v[8:11], v[152:155], v[208:211], v[8:11]
	s_setprio 0
	s_setprio 1
	v_mfma_f32_16x16x32_bf16 v[52:55], v[156:159], v[180:183], v[52:55]
	v_mfma_f32_16x16x32_bf16 v[52:55], v[160:163], v[184:187], v[52:55]
	v_mfma_f32_16x16x32_bf16 v[44:47], v[164:167], v[180:183], v[44:47]
	v_mfma_f32_16x16x32_bf16 v[44:47], v[176:179], v[184:187], v[44:47]
	v_mfma_f32_16x16x32_bf16 v[36:39], v[156:159], v[188:191], v[36:39]
	v_mfma_f32_16x16x32_bf16 v[36:39], v[160:163], v[192:195], v[36:39]
	v_mfma_f32_16x16x32_bf16 v[28:31], v[164:167], v[188:191], v[28:31]
	v_mfma_f32_16x16x32_bf16 v[28:31], v[176:179], v[192:195], v[28:31]
	v_mfma_f32_16x16x32_bf16 v[20:23], v[156:159], v[196:199], v[20:23]
	v_mfma_f32_16x16x32_bf16 v[20:23], v[160:163], v[200:203], v[20:23]
	v_mfma_f32_16x16x32_bf16 v[12:15], v[164:167], v[196:199], v[12:15]
	v_mfma_f32_16x16x32_bf16 v[12:15], v[176:179], v[200:203], v[12:15]
	v_mfma_f32_16x16x32_bf16 v[4:7], v[156:159], v[204:207], v[4:7]
	v_mfma_f32_16x16x32_bf16 v[4:7], v[160:163], v[208:211], v[4:7]
	v_mfma_f32_16x16x32_bf16 v[0:3], v[164:167], v[204:207], v[0:3]
	v_mfma_f32_16x16x32_bf16 v[0:3], v[176:179], v[208:211], v[0:3]
	s_setprio 0
	s_barrier
	s_add_i32 s31, 0, 0x18000
	s_add_i32 s44, 0, 0x1c000
	s_add_u32 s42, s42, 0x4000
	s_addc_u32 s43, s43, 0
	s_mov_b32 m0, s19
	v_lshl_add_u64 v[212:213], s[42:43], 0, v[140:141]
	global_load_lds_dwordx4 v[212:213], off
	v_lshl_add_u64 v[212:213], s[42:43], 0, v[138:139]
	s_mov_b32 m0, s20
	s_nop 0
	global_load_lds_dwordx4 v[212:213], off
	v_add_u32_e32 v152, s31, v169
	v_add_u32_e32 v175, s44, v169
	ds_read_b128 v[128:131], v152
	ds_read_b128 v[132:135], v152 offset:1024
	ds_read_b128 v[148:151], v152 offset:2048
	ds_read_b128 v[152:155], v152 offset:3072
	ds_read_b128 v[156:159], v175
	ds_read_b128 v[160:163], v175 offset:1024
	ds_read_b128 v[164:167], v175 offset:2048
	ds_read_b128 v[176:179], v175 offset:3072
	ds_read_b128 v[180:183], v174 offset:32768
	ds_read_b128 v[184:187], v174 offset:33792
	ds_read_b128 v[188:191], v174 offset:34816
	ds_read_b128 v[192:195], v174 offset:35840
	ds_read_b128 v[196:199], v174 offset:36864
	ds_read_b128 v[200:203], v174 offset:37888
	ds_read_b128 v[204:207], v174 offset:38912
	ds_read_b128 v[208:211], v174 offset:39936
	s_waitcnt vmcnt(8)
	s_waitcnt lgkmcnt(0)
	s_barrier
	s_setprio 1
	s_waitcnt lgkmcnt(0)
	v_mfma_f32_16x16x32_bf16 v[124:127], v[128:131], v[180:183], v[124:127]
	v_mfma_f32_16x16x32_bf16 v[124:127], v[132:135], v[184:187], v[124:127]
	v_mfma_f32_16x16x32_bf16 v[120:123], v[148:151], v[180:183], v[120:123]
	v_mfma_f32_16x16x32_bf16 v[120:123], v[152:155], v[184:187], v[120:123]
	v_mfma_f32_16x16x32_bf16 v[108:111], v[128:131], v[188:191], v[108:111]
	v_mfma_f32_16x16x32_bf16 v[108:111], v[132:135], v[192:195], v[108:111]
	v_mfma_f32_16x16x32_bf16 v[104:107], v[148:151], v[188:191], v[104:107]
	v_mfma_f32_16x16x32_bf16 v[104:107], v[152:155], v[192:195], v[104:107]
	v_mfma_f32_16x16x32_bf16 v[92:95], v[128:131], v[196:199], v[92:95]
	v_mfma_f32_16x16x32_bf16 v[92:95], v[132:135], v[200:203], v[92:95]
	v_mfma_f32_16x16x32_bf16 v[88:91], v[148:151], v[196:199], v[88:91]
	v_mfma_f32_16x16x32_bf16 v[88:91], v[152:155], v[200:203], v[88:91]
	v_mfma_f32_16x16x32_bf16 v[76:79], v[128:131], v[204:207], v[76:79]
	v_mfma_f32_16x16x32_bf16 v[76:79], v[132:135], v[208:211], v[76:79]
	v_mfma_f32_16x16x32_bf16 v[72:75], v[148:151], v[204:207], v[72:75]
	v_mfma_f32_16x16x32_bf16 v[72:75], v[152:155], v[208:211], v[72:75]
	s_setprio 0
	s_setprio 1
	v_mfma_f32_16x16x32_bf16 v[116:119], v[156:159], v[180:183], v[116:119]
	v_mfma_f32_16x16x32_bf16 v[116:119], v[160:163], v[184:187], v[116:119]
	v_mfma_f32_16x16x32_bf16 v[112:115], v[164:167], v[180:183], v[112:115]
	v_mfma_f32_16x16x32_bf16 v[112:115], v[176:179], v[184:187], v[112:115]
	v_mfma_f32_16x16x32_bf16 v[100:103], v[156:159], v[188:191], v[100:103]
	v_mfma_f32_16x16x32_bf16 v[100:103], v[160:163], v[192:195], v[100:103]
	v_mfma_f32_16x16x32_bf16 v[96:99], v[164:167], v[188:191], v[96:99]
	v_mfma_f32_16x16x32_bf16 v[96:99], v[176:179], v[192:195], v[96:99]
	v_mfma_f32_16x16x32_bf16 v[84:87], v[156:159], v[196:199], v[84:87]
	v_mfma_f32_16x16x32_bf16 v[84:87], v[160:163], v[200:203], v[84:87]
	v_mfma_f32_16x16x32_bf16 v[80:83], v[164:167], v[196:199], v[80:83]
	v_mfma_f32_16x16x32_bf16 v[80:83], v[176:179], v[200:203], v[80:83]
	v_mfma_f32_16x16x32_bf16 v[68:71], v[156:159], v[204:207], v[68:71]
	v_mfma_f32_16x16x32_bf16 v[68:71], v[160:163], v[208:211], v[68:71]
	v_mfma_f32_16x16x32_bf16 v[64:67], v[164:167], v[204:207], v[64:67]
	v_mfma_f32_16x16x32_bf16 v[64:67], v[176:179], v[208:211], v[64:67]
	s_setprio 0
	s_barrier
; #define PG8_STAGE(bufoff, gbase, voff) do { _Pragma("unroll") for (int _i = 0; _i < 2; ++_i) \
;         __builtin_amdgcn_global_load_lds((const unsigned*)((const char*)(gbase) + (voff)[_i]), (PG8_LAS unsigned*)(lds + (bufoff) + ldsw + _i * 8192), 16, 0, 0); } while (0)
; #define PG8_LDA(dst, b, h) do { _Pragma("unroll") for (int m = 0; m < 4; ++m) _Pragma("unroll") for (int k = 0; k < 2; ++k) dst[m][k] = *(const PG8_LAS bf16x8*)(lds + PG8_SA(b, h) + aoff + m * 2048 + k * 1024); } while (0)
; #define PG8_MMA(ai, bj, At, Bt) do { __builtin_amdgcn_s_setprio(1); _Pragma("unroll") for (int m = 0; m < 4; ++m) _Pragma("unroll") for (int n = 0; n < 2; ++n) _Pragma("unroll") for (int k = 0; k < 2; ++k) \
;         acc[ai][bj][m][n] = __builtin_amdgcn_mfma_f32_16x16x32_bf16(Bt[n][k], At[m][k], acc[ai][bj][m][n], 0, 0, 0); __builtin_amdgcn_s_setprio(0); } while (0)
; #define PG8_WAIT_V(n) asm volatile("s_waitcnt vmcnt(" #n ")" ::: "memory")
; #define PG8_WAIT_L(n) asm volatile("s_waitcnt lgkmcnt(" #n ")" ::: "memory")
; #define PG8_BAR __builtin_amdgcn_s_barrier()
; #define PG8_SCHED __builtin_amdgcn_sched_barrier(0)
; template <class Epi, class Sched, bool ALIGN_EPI = false, bool SP2 = false>
; __device__ __forceinline__ void gemm_phase(PG8_LAS unsigned char* lds, const Gemm g, const Sched& S, const Epi& E) {
;     ...
;             PG8_LDA(At, 1, 1); PG8_STAGE(PG8_SB(1, 0), b3, voffB); PG8_STAGE(PG8_SB(1, 1), b3 + hstepB, voffB); PG8_STAGE(PG8_SA(1, 0), a3, voffA);
;             PG8_WAIT_V(8); PG8_WAIT_L(0); PG8_BAR; PG8_MMA(1, 0, At, B0); PG8_MMA(1, 1, At, B1); PG8_BAR; PG8_SCHED;
	s_add_u32 s42, s40, 0x8000
	s_addc_u32 s43, s41, 0
	s_add_i32 s31, s31, s14
	v_lshl_add_u64 v[212:213], s[42:43], 0, v[220:221]
	s_mov_b32 m0, s31
	ds_read_b128 v[180:183], v174 offset:49152
	ds_read_b128 v[184:187], v174 offset:50176
	ds_read_b128 v[188:191], v174 offset:51200
	ds_read_b128 v[192:195], v174 offset:52224
	ds_read_b128 v[196:199], v174 offset:53248
	ds_read_b128 v[200:203], v174 offset:54272
	ds_read_b128 v[204:207], v174 offset:55296
	ds_read_b128 v[208:211], v174 offset:56320
	global_load_lds_dwordx4 v[212:213], off
	s_add_i32 m0, s31, 0x2000
	s_add_u32 s40, s40, 0xc000
	v_lshl_add_u64 v[212:213], s[42:43], 0, v[136:137]
	s_addc_u32 s41, s41, 0
	s_add_i32 s31, s44, s14
	global_load_lds_dwordx4 v[212:213], off
	v_lshl_add_u64 v[212:213], s[40:41], 0, v[220:221]
	s_mov_b32 m0, s31
	s_nop 0
	global_load_lds_dwordx4 v[212:213], off
	v_lshl_add_u64 v[212:213], s[40:41], 0, v[136:137]
	s_add_i32 m0, s31, 0x2000
	s_nop 0
	global_load_lds_dwordx4 v[212:213], off
	v_lshl_add_u64 v[212:213], s[38:39], 0, v[140:141]
	s_mov_b32 m0, s21
	s_nop 0
	global_load_lds_dwordx4 v[212:213], off
	v_lshl_add_u64 v[212:213], s[38:39], 0, v[138:139]
	s_mov_b32 m0, s22
	s_nop 0
	global_load_lds_dwordx4 v[212:213], off
	s_waitcnt vmcnt(8)
	s_waitcnt lgkmcnt(0)
	s_barrier
	s_setprio 1
	s_waitcnt lgkmcnt(0)
	v_mfma_f32_16x16x32_bf16 v[60:63], v[128:131], v[180:183], v[60:63]
	v_mfma_f32_16x16x32_bf16 v[60:63], v[132:135], v[184:187], v[60:63]
	v_mfma_f32_16x16x32_bf16 v[56:59], v[148:151], v[180:183], v[56:59]
	v_mfma_f32_16x16x32_bf16 v[56:59], v[152:155], v[184:187], v[56:59]
	v_mfma_f32_16x16x32_bf16 v[48:51], v[128:131], v[188:191], v[48:51]
	v_mfma_f32_16x16x32_bf16 v[48:51], v[132:135], v[192:195], v[48:51]
	v_mfma_f32_16x16x32_bf16 v[40:43], v[148:151], v[188:191], v[40:43]
	v_mfma_f32_16x16x32_bf16 v[40:43], v[152:155], v[192:195], v[40:43]
	v_mfma_f32_16x16x32_bf16 v[32:35], v[128:131], v[196:199], v[32:35]
	v_mfma_f32_16x16x32_bf16 v[32:35], v[132:135], v[200:203], v[32:35]
	v_mfma_f32_16x16x32_bf16 v[24:27], v[148:151], v[196:199], v[24:27]
	v_mfma_f32_16x16x32_bf16 v[24:27], v[152:155], v[200:203], v[24:27]
	v_mfma_f32_16x16x32_bf16 v[16:19], v[128:131], v[204:207], v[16:19]
	v_mfma_f32_16x16x32_bf16 v[16:19], v[132:135], v[208:211], v[16:19]
	v_mfma_f32_16x16x32_bf16 v[8:11], v[148:151], v[204:207], v[8:11]
	v_mfma_f32_16x16x32_bf16 v[8:11], v[152:155], v[208:211], v[8:11]
	s_setprio 0
	s_setprio 1
	v_mfma_f32_16x16x32_bf16 v[52:55], v[156:159], v[180:183], v[52:55]
	v_mfma_f32_16x16x32_bf16 v[52:55], v[160:163], v[184:187], v[52:55]
	v_mfma_f32_16x16x32_bf16 v[44:47], v[164:167], v[180:183], v[44:47]
	v_mfma_f32_16x16x32_bf16 v[44:47], v[176:179], v[184:187], v[44:47]
	v_mfma_f32_16x16x32_bf16 v[36:39], v[156:159], v[188:191], v[36:39]
	v_mfma_f32_16x16x32_bf16 v[36:39], v[160:163], v[192:195], v[36:39]
	v_mfma_f32_16x16x32_bf16 v[28:31], v[164:167], v[188:191], v[28:31]
	v_mfma_f32_16x16x32_bf16 v[28:31], v[176:179], v[192:195], v[28:31]
	v_mfma_f32_16x16x32_bf16 v[20:23], v[156:159], v[196:199], v[20:23]
	v_mfma_f32_16x16x32_bf16 v[20:23], v[160:163], v[200:203], v[20:23]
	v_mfma_f32_16x16x32_bf16 v[12:15], v[164:167], v[196:199], v[12:15]
	v_mfma_f32_16x16x32_bf16 v[12:15], v[176:179], v[200:203], v[12:15]
	v_mfma_f32_16x16x32_bf16 v[4:7], v[156:159], v[204:207], v[4:7]
	v_mfma_f32_16x16x32_bf16 v[4:7], v[160:163], v[208:211], v[4:7]
	v_mfma_f32_16x16x32_bf16 v[0:3], v[164:167], v[204:207], v[0:3]
	v_mfma_f32_16x16x32_bf16 v[0:3], v[176:179], v[208:211], v[0:3]
	s_setprio 0
	s_barrier
	s_add_i32 s30, s30, 2
	s_add_u32 s36, s36, 0x10000
	s_addc_u32 s37, s37, 0
	s_add_u32 s28, s28, 0x10000
	s_addc_u32 s29, s29, 0
	s_cmp_gt_u32 s30, 29
	s_cbranch_scc0 .LBB0_232
	s_and_b64 vcc, exec, s[8:9]
	s_cbranch_vccz .LBB0_235
	s_barrier

; #define PG8_STAGE(bufoff, gbase, voff) do { _Pragma("unroll") for (int _i = 0; _i < 2; ++_i) \
;         __builtin_amdgcn_global_load_lds((const unsigned*)((const char*)(gbase) + (voff)[_i]), (PG8_LAS unsigned*)(lds + (bufoff) + ldsw + _i * 8192), 16, 0, 0); } while (0)
; #define PG8_LDA(dst, b, h) do { _Pragma("unroll") for (int m = 0; m < 4; ++m) _Pragma("unroll") for (int k = 0; k < 2; ++k) dst[m][k] = *(const PG8_LAS bf16x8*)(lds + PG8_SA(b, h) + aoff + m * 2048 + k * 1024); } while (0)
; #define PG8_LDB(dst, b, h) do { _Pragma("unroll") for (int n = 0; n < 2; ++n) _Pragma("unroll") for (int k = 0; k < 2; ++k) dst[n][k] = *(const PG8_LAS bf16x8*)(lds + PG8_SB(b, h) + boff + n * 2048 + k * 1024); } while (0)
; #define PG8_MMA(ai, bj, At, Bt) do { __builtin_amdgcn_s_setprio(1); _Pragma("unroll") for (int m = 0; m < 4; ++m) _Pragma("unroll") for (int n = 0; n < 2; ++n) _Pragma("unroll") for (int k = 0; k < 2; ++k) \
;         acc[ai][bj][m][n] = __builtin_amdgcn_mfma_f32_16x16x32_bf16(Bt[n][k], At[m][k], acc[ai][bj][m][n], 0, 0, 0); __builtin_amdgcn_s_setprio(0); } while (0)
; #define PG8_WAIT_V(n) asm volatile("s_waitcnt vmcnt(" #n ")" ::: "memory")
; #define PG8_WAIT_L(n) asm volatile("s_waitcnt lgkmcnt(" #n ")" ::: "memory")
; template <class Epi, class Sched, bool ALIGN_EPI = false, bool SP2 = false>
; __device__ __forceinline__ void gemm_phase(PG8_LAS unsigned char* lds, const Gemm g, const Sched& S, const Epi& E) {
;     ...
;             const bool last = (t == nt - 2);
;             const char* a1 = cA + (size_t)(t + 1) * kstepB;
;             const char* a2 = last ? nA : cA + (size_t)(t + 2) * kstepB; const char* b2 = last ? nB : cB + (size_t)(t + 2) * kstepB;
;             const char* a3 = a2 + kstepB; const char* b3 = b2 + kstepB;
;             if (last && has_next) S.a_ready(nxt);
;             if constexpr (SP2) {
;             PG8_LDB(B0, 0, 0); PG8_LDB(B1, 0, 1); PG8_SCHED; PG8_LDA(At, 0, 0); PG8_STAGE(PG8_SA(1, 1), a1 + hstepB, voffA);
;             PG8_WAIT_V(8); PG8_WAIT_L(0); PG8_BAR; PG8_MMA(0, 0, At, B0); PG8_MMA(0, 1, At, B1); PG8_BAR; PG8_SCHED;
;             PG8_LDA(At, 0, 1); PG8_STAGE(PG8_SB(0, 0), b2, voffB); PG8_STAGE(PG8_SB(0, 1), b2 + hstepB, voffB); PG8_STAGE(PG8_SA(0, 0), a2, voffA);
;             PG8_WAIT_V(8); PG8_WAIT_L(0); PG8_BAR; PG8_MMA(1, 0, At, B0); PG8_MMA(1, 1, At, B1); PG8_BAR; PG8_SCHED;
.LBB0_263:
	s_add_u32 s38, s36, 0x4000
	s_addc_u32 s39, s37, 0
	s_cmp_eq_u32 s62, 28
	s_cselect_b32 s42, s30, s38
	s_cselect_b32 s43, s13, s39
	s_cselect_b32 s40, s31, s44
	s_cselect_b32 s41, s11, s45
	s_add_u32 s38, s42, 0x8000
	s_addc_u32 s39, s43, 0
	s_add_i32 s63, 0, 0x10000
	s_add_i32 s75, 0, 0x14000
	v_lshl_add_u64 v[214:215], s[36:37], 0, v[146:147]
	s_add_i32 m0, s19, 0xc000
	s_nop 0
	global_load_lds_dwordx4 v[214:215], off
	v_lshl_add_u64 v[214:215], s[36:37], 0, v[148:149]
	s_add_i32 m0, s19, 0xe000
	s_nop 0
	global_load_lds_dwordx4 v[214:215], off
	v_add_u32_e32 v151, s63, v165
	ds_read_b128 v[128:131], v151
	ds_read_b128 v[132:135], v151 offset:1024
	ds_read_b128 v[152:155], v151 offset:2048
	ds_read_b128 v[156:159], v151 offset:3072
	v_add_u32_e32 v151, s75, v165
	ds_read_b128 v[160:163], v151
	ds_read_b128 v[170:173], v151 offset:1024
	ds_read_b128 v[174:177], v151 offset:2048
	ds_read_b128 v[178:181], v151 offset:3072
	ds_read_b128 v[182:185], v168
	ds_read_b128 v[186:189], v168 offset:1024
	ds_read_b128 v[190:193], v168 offset:2048
	ds_read_b128 v[194:197], v168 offset:3072
	ds_read_b128 v[198:201], v168 offset:4096
	ds_read_b128 v[202:205], v168 offset:5120
	ds_read_b128 v[206:209], v168 offset:6144
	ds_read_b128 v[210:213], v168 offset:7168
	s_waitcnt vmcnt(8)
	s_waitcnt lgkmcnt(0)
	s_barrier
	s_setprio 1
	s_waitcnt lgkmcnt(0)
	v_mfma_f32_16x16x32_bf16 v[124:127], v[128:131], v[182:185], v[124:127]
	v_mfma_f32_16x16x32_bf16 v[124:127], v[132:135], v[186:189], v[124:127]
	v_mfma_f32_16x16x32_bf16 v[116:119], v[152:155], v[182:185], v[116:119]
	v_mfma_f32_16x16x32_bf16 v[116:119], v[156:159], v[186:189], v[116:119]
	v_mfma_f32_16x16x32_bf16 v[108:111], v[128:131], v[190:193], v[108:111]
	v_mfma_f32_16x16x32_bf16 v[108:111], v[132:135], v[194:197], v[108:111]
	v_mfma_f32_16x16x32_bf16 v[100:103], v[152:155], v[190:193], v[100:103]
	v_mfma_f32_16x16x32_bf16 v[100:103], v[156:159], v[194:197], v[100:103]
	v_mfma_f32_16x16x32_bf16 v[92:95], v[128:131], v[198:201], v[92:95]
	v_mfma_f32_16x16x32_bf16 v[92:95], v[132:135], v[202:205], v[92:95]
	v_mfma_f32_16x16x32_bf16 v[84:87], v[152:155], v[198:201], v[84:87]
	v_mfma_f32_16x16x32_bf16 v[84:87], v[156:159], v[202:205], v[84:87]
	v_mfma_f32_16x16x32_bf16 v[76:79], v[128:131], v[206:209], v[76:79]
	v_mfma_f32_16x16x32_bf16 v[76:79], v[132:135], v[210:213], v[76:79]
	v_mfma_f32_16x16x32_bf16 v[68:71], v[152:155], v[206:209], v[68:71]
	v_mfma_f32_16x16x32_bf16 v[68:71], v[156:159], v[210:213], v[68:71]
	s_setprio 0
	s_setprio 1
	v_mfma_f32_16x16x32_bf16 v[120:123], v[160:163], v[182:185], v[120:123]
	v_mfma_f32_16x16x32_bf16 v[120:123], v[170:173], v[186:189], v[120:123]
	v_mfma_f32_16x16x32_bf16 v[112:115], v[174:177], v[182:185], v[112:115]
	v_mfma_f32_16x16x32_bf16 v[112:115], v[178:181], v[186:189], v[112:115]
	v_mfma_f32_16x16x32_bf16 v[104:107], v[160:163], v[190:193], v[104:107]
	v_mfma_f32_16x16x32_bf16 v[104:107], v[170:173], v[194:197], v[104:107]
	v_mfma_f32_16x16x32_bf16 v[96:99], v[174:177], v[190:193], v[96:99]
	v_mfma_f32_16x16x32_bf16 v[96:99], v[178:181], v[194:197], v[96:99]
	v_mfma_f32_16x16x32_bf16 v[88:91], v[160:163], v[198:201], v[88:91]
	v_mfma_f32_16x16x32_bf16 v[88:91], v[170:173], v[202:205], v[88:91]
	v_mfma_f32_16x16x32_bf16 v[80:83], v[174:177], v[198:201], v[80:83]
	v_mfma_f32_16x16x32_bf16 v[80:83], v[178:181], v[202:205], v[80:83]
	v_mfma_f32_16x16x32_bf16 v[72:75], v[160:163], v[206:209], v[72:75]
	v_mfma_f32_16x16x32_bf16 v[72:75], v[170:173], v[210:213], v[72:75]
	v_mfma_f32_16x16x32_bf16 v[64:67], v[174:177], v[206:209], v[64:67]
	v_mfma_f32_16x16x32_bf16 v[64:67], v[178:181], v[210:213], v[64:67]
	s_setprio 0
	s_barrier
	s_add_i32 s63, s63, s16
	v_lshl_add_u64 v[214:215], s[40:41], 0, v[140:141]
	s_mov_b32 m0, s63
	ds_read_b128 v[182:185], v168 offset:16384
	ds_read_b128 v[186:189], v168 offset:17408
	ds_read_b128 v[190:193], v168 offset:18432
	ds_read_b128 v[194:197], v168 offset:19456
	ds_read_b128 v[198:201], v168 offset:20480
	ds_read_b128 v[202:205], v168 offset:21504
	ds_read_b128 v[206:209], v168 offset:22528
	ds_read_b128 v[210:213], v168 offset:23552
	global_load_lds_dwordx4 v[214:215], off
	s_add_i32 m0, s63, 0x2000
	s_add_u32 s66, s40, 0x4000
	v_lshl_add_u64 v[214:215], s[40:41], 0, v[136:137]
	s_addc_u32 s67, s41, 0
	s_add_i32 s63, s75, s16
	global_load_lds_dwordx4 v[214:215], off
	v_lshl_add_u64 v[214:215], s[66:67], 0, v[140:141]
	s_mov_b32 m0, s63
	s_nop 0
	global_load_lds_dwordx4 v[214:215], off
	v_lshl_add_u64 v[214:215], s[66:67], 0, v[136:137]
	s_add_i32 m0, s63, 0x2000
	s_nop 0
	global_load_lds_dwordx4 v[214:215], off
	v_lshl_add_u64 v[214:215], s[42:43], 0, v[142:143]
	s_mov_b32 m0, s19
	s_nop 0
	global_load_lds_dwordx4 v[214:215], off
	v_lshl_add_u64 v[214:215], s[42:43], 0, v[138:139]
	s_mov_b32 m0, s20
	s_nop 0
	global_load_lds_dwordx4 v[214:215], off
	s_waitcnt vmcnt(8)
	s_waitcnt lgkmcnt(0)
	s_barrier
; #define PG8_STAGE(bufoff, gbase, voff) do { _Pragma("unroll") for (int _i = 0; _i < 2; ++_i) \
;         __builtin_amdgcn_global_load_lds((const unsigned*)((const char*)(gbase) + (voff)[_i]), (PG8_LAS unsigned*)(lds + (bufoff) + ldsw + _i * 8192), 16, 0, 0); } while (0)
; #define PG8_LDA(dst, b, h) do { _Pragma("unroll") for (int m = 0; m < 4; ++m) _Pragma("unroll") for (int k = 0; k < 2; ++k) dst[m][k] = *(const PG8_LAS bf16x8*)(lds + PG8_SA(b, h) + aoff + m * 2048 + k * 1024); } while (0)
; #define PG8_LDB(dst, b, h) do { _Pragma("unroll") for (int n = 0; n < 2; ++n) _Pragma("unroll") for (int k = 0; k < 2; ++k) dst[n][k] = *(const PG8_LAS bf16x8*)(lds + PG8_SB(b, h) + boff + n * 2048 + k * 1024); } while (0)
; #define PG8_MMA(ai, bj, At, Bt) do { __builtin_amdgcn_s_setprio(1); _Pragma("unroll") for (int m = 0; m < 4; ++m) _Pragma("unroll") for (int n = 0; n < 2; ++n) _Pragma("unroll") for (int k = 0; k < 2; ++k) \
;         acc[ai][bj][m][n] = __builtin_amdgcn_mfma_f32_16x16x32_bf16(Bt[n][k], At[m][k], acc[ai][bj][m][n], 0, 0, 0); __builtin_amdgcn_s_setprio(0); } while (0)
; #define PG8_WAIT_V(n) asm volatile("s_waitcnt vmcnt(" #n ")" ::: "memory")
; #define PG8_WAIT_L(n) asm volatile("s_waitcnt lgkmcnt(" #n ")" ::: "memory")
; #define PG8_BAR __builtin_amdgcn_s_barrier()
; #define PG8_SCHED __builtin_amdgcn_sched_barrier(0)
; template <class Epi, class Sched, bool ALIGN_EPI = false, bool SP2 = false>
; __device__ __forceinline__ void gemm_phase(PG8_LAS unsigned char* lds, const Gemm g, const Sched& S, const Epi& E) {
;     ...
;             PG8_WAIT_V(8); PG8_WAIT_L(0); PG8_BAR; PG8_MMA(1, 0, At, B0); PG8_MMA(1, 1, At, B1); PG8_BAR; PG8_SCHED;
;             PG8_LDB(B0, 1, 0); PG8_LDB(B1, 1, 1); PG8_SCHED; PG8_LDA(At, 1, 0); PG8_STAGE(PG8_SA(0, 1), a2 + hstepB, voffA);
;             PG8_WAIT_V(8); PG8_WAIT_L(0); PG8_BAR; PG8_MMA(0, 0, At, B0); PG8_MMA(0, 1, At, B1); PG8_BAR; PG8_SCHED;
	s_setprio 1
	s_waitcnt lgkmcnt(0)
	v_mfma_f32_16x16x32_bf16 v[60:63], v[128:131], v[182:185], v[60:63]
	v_mfma_f32_16x16x32_bf16 v[60:63], v[132:135], v[186:189], v[60:63]
	v_mfma_f32_16x16x32_bf16 v[52:55], v[152:155], v[182:185], v[52:55]
	v_mfma_f32_16x16x32_bf16 v[52:55], v[156:159], v[186:189], v[52:55]
	v_mfma_f32_16x16x32_bf16 v[44:47], v[128:131], v[190:193], v[44:47]
	v_mfma_f32_16x16x32_bf16 v[44:47], v[132:135], v[194:197], v[44:47]
	v_mfma_f32_16x16x32_bf16 v[36:39], v[152:155], v[190:193], v[36:39]
	v_mfma_f32_16x16x32_bf16 v[36:39], v[156:159], v[194:197], v[36:39]
	v_mfma_f32_16x16x32_bf16 v[28:31], v[128:131], v[198:201], v[28:31]
	v_mfma_f32_16x16x32_bf16 v[28:31], v[132:135], v[202:205], v[28:31]
	v_mfma_f32_16x16x32_bf16 v[20:23], v[152:155], v[198:201], v[20:23]
	v_mfma_f32_16x16x32_bf16 v[20:23], v[156:159], v[202:205], v[20:23]
	v_mfma_f32_16x16x32_bf16 v[12:15], v[128:131], v[206:209], v[12:15]
	v_mfma_f32_16x16x32_bf16 v[12:15], v[132:135], v[210:213], v[12:15]
	v_mfma_f32_16x16x32_bf16 v[4:7], v[152:155], v[206:209], v[4:7]
	v_mfma_f32_16x16x32_bf16 v[4:7], v[156:159], v[210:213], v[4:7]
	s_setprio 0
	s_setprio 1
	v_mfma_f32_16x16x32_bf16 v[56:59], v[160:163], v[182:185], v[56:59]
	v_mfma_f32_16x16x32_bf16 v[56:59], v[170:173], v[186:189], v[56:59]
	v_mfma_f32_16x16x32_bf16 v[48:51], v[174:177], v[182:185], v[48:51]
	v_mfma_f32_16x16x32_bf16 v[48:51], v[178:181], v[186:189], v[48:51]
	v_mfma_f32_16x16x32_bf16 v[40:43], v[160:163], v[190:193], v[40:43]
	v_mfma_f32_16x16x32_bf16 v[40:43], v[170:173], v[194:197], v[40:43]
	v_mfma_f32_16x16x32_bf16 v[32:35], v[174:177], v[190:193], v[32:35]
	v_mfma_f32_16x16x32_bf16 v[32:35], v[178:181], v[194:197], v[32:35]
	v_mfma_f32_16x16x32_bf16 v[24:27], v[160:163], v[198:201], v[24:27]
	v_mfma_f32_16x16x32_bf16 v[24:27], v[170:173], v[202:205], v[24:27]
	v_mfma_f32_16x16x32_bf16 v[16:19], v[174:177], v[198:201], v[16:19]
	v_mfma_f32_16x16x32_bf16 v[16:19], v[178:181], v[202:205], v[16:19]
	v_mfma_f32_16x16x32_bf16 v[8:11], v[160:163], v[206:209], v[8:11]
	v_mfma_f32_16x16x32_bf16 v[8:11], v[170:173], v[210:213], v[8:11]
	v_mfma_f32_16x16x32_bf16 v[0:3], v[174:177], v[206:209], v[0:3]
	v_mfma_f32_16x16x32_bf16 v[0:3], v[178:181], v[210:213], v[0:3]
	s_setprio 0
	s_barrier
	s_add_i32 s63, 0, 0x18000
	s_add_i32 s66, 0, 0x1c000
	s_add_u32 s42, s42, 0x4000
	s_addc_u32 s43, s43, 0
	s_mov_b32 m0, s21
	v_lshl_add_u64 v[214:215], s[42:43], 0, v[142:143]
	global_load_lds_dwordx4 v[214:215], off
	v_lshl_add_u64 v[214:215], s[42:43], 0, v[138:139]
	s_mov_b32 m0, s22
	s_nop 0
	global_load_lds_dwordx4 v[214:215], off
	v_add_u32_e32 v151, s63, v165
	ds_read_b128 v[128:131], v151
	ds_read_b128 v[132:135], v151 offset:1024
	ds_read_b128 v[152:155], v151 offset:2048
	ds_read_b128 v[156:159], v151 offset:3072
	v_add_u32_e32 v151, s66, v165
	ds_read_b128 v[160:163], v151
	ds_read_b128 v[170:173], v151 offset:1024
	ds_read_b128 v[174:177], v151 offset:2048
	ds_read_b128 v[178:181], v151 offset:3072
	ds_read_b128 v[182:185], v168 offset:32768
	ds_read_b128 v[186:189], v168 offset:33792
	ds_read_b128 v[190:193], v168 offset:34816
	ds_read_b128 v[194:197], v168 offset:35840
	ds_read_b128 v[198:201], v168 offset:36864
	ds_read_b128 v[202:205], v168 offset:37888
	ds_read_b128 v[206:209], v168 offset:38912
	ds_read_b128 v[210:213], v168 offset:39936
	s_waitcnt vmcnt(8)
	s_waitcnt lgkmcnt(0)
	s_barrier
	s_setprio 1
	s_waitcnt lgkmcnt(0)
	v_mfma_f32_16x16x32_bf16 v[124:127], v[128:131], v[182:185], v[124:127]
	v_mfma_f32_16x16x32_bf16 v[124:127], v[132:135], v[186:189], v[124:127]
	v_mfma_f32_16x16x32_bf16 v[116:119], v[152:155], v[182:185], v[116:119]
	v_mfma_f32_16x16x32_bf16 v[116:119], v[156:159], v[186:189], v[116:119]
	v_mfma_f32_16x16x32_bf16 v[108:111], v[128:131], v[190:193], v[108:111]
	v_mfma_f32_16x16x32_bf16 v[108:111], v[132:135], v[194:197], v[108:111]
	v_mfma_f32_16x16x32_bf16 v[100:103], v[152:155], v[190:193], v[100:103]
	v_mfma_f32_16x16x32_bf16 v[100:103], v[156:159], v[194:197], v[100:103]
	v_mfma_f32_16x16x32_bf16 v[92:95], v[128:131], v[198:201], v[92:95]
	v_mfma_f32_16x16x32_bf16 v[92:95], v[132:135], v[202:205], v[92:95]
	v_mfma_f32_16x16x32_bf16 v[84:87], v[152:155], v[198:201], v[84:87]
	v_mfma_f32_16x16x32_bf16 v[84:87], v[156:159], v[202:205], v[84:87]
	v_mfma_f32_16x16x32_bf16 v[76:79], v[128:131], v[206:209], v[76:79]
	v_mfma_f32_16x16x32_bf16 v[76:79], v[132:135], v[210:213], v[76:79]
	v_mfma_f32_16x16x32_bf16 v[68:71], v[152:155], v[206:209], v[68:71]
	v_mfma_f32_16x16x32_bf16 v[68:71], v[156:159], v[210:213], v[68:71]
	s_setprio 0
	s_setprio 1
	v_mfma_f32_16x16x32_bf16 v[120:123], v[160:163], v[182:185], v[120:123]
	v_mfma_f32_16x16x32_bf16 v[120:123], v[170:173], v[186:189], v[120:123]
	v_mfma_f32_16x16x32_bf16 v[112:115], v[174:177], v[182:185], v[112:115]
	v_mfma_f32_16x16x32_bf16 v[112:115], v[178:181], v[186:189], v[112:115]
	v_mfma_f32_16x16x32_bf16 v[104:107], v[160:163], v[190:193], v[104:107]
	v_mfma_f32_16x16x32_bf16 v[104:107], v[170:173], v[194:197], v[104:107]
	v_mfma_f32_16x16x32_bf16 v[96:99], v[174:177], v[190:193], v[96:99]
	v_mfma_f32_16x16x32_bf16 v[96:99], v[178:181], v[194:197], v[96:99]
	v_mfma_f32_16x16x32_bf16 v[88:91], v[160:163], v[198:201], v[88:91]
	v_mfma_f32_16x16x32_bf16 v[88:91], v[170:173], v[202:205], v[88:91]
	v_mfma_f32_16x16x32_bf16 v[80:83], v[174:177], v[198:201], v[80:83]
	v_mfma_f32_16x16x32_bf16 v[80:83], v[178:181], v[202:205], v[80:83]
	v_mfma_f32_16x16x32_bf16 v[72:75], v[160:163], v[206:209], v[72:75]
	v_mfma_f32_16x16x32_bf16 v[72:75], v[170:173], v[210:213], v[72:75]
	v_mfma_f32_16x16x32_bf16 v[64:67], v[174:177], v[206:209], v[64:67]
	v_mfma_f32_16x16x32_bf16 v[64:67], v[178:181], v[210:213], v[64:67]
	s_setprio 0
	s_barrier
; #define PG8_STAGE(bufoff, gbase, voff) do { _Pragma("unroll") for (int _i = 0; _i < 2; ++_i) \
;         __builtin_amdgcn_global_load_lds((const unsigned*)((const char*)(gbase) + (voff)[_i]), (PG8_LAS unsigned*)(lds + (bufoff) + ldsw + _i * 8192), 16, 0, 0); } while (0)
; #define PG8_LDA(dst, b, h) do { _Pragma("unroll") for (int m = 0; m < 4; ++m) _Pragma("unroll") for (int k = 0; k < 2; ++k) dst[m][k] = *(const PG8_LAS bf16x8*)(lds + PG8_SA(b, h) + aoff + m * 2048 + k * 1024); } while (0)
; #define PG8_MMA(ai, bj, At, Bt) do { __builtin_amdgcn_s_setprio(1); _Pragma("unroll") for (int m = 0; m < 4; ++m) _Pragma("unroll") for (int n = 0; n < 2; ++n) _Pragma("unroll") for (int k = 0; k < 2; ++k) \
;         acc[ai][bj][m][n] = __builtin_amdgcn_mfma_f32_16x16x32_bf16(Bt[n][k], At[m][k], acc[ai][bj][m][n], 0, 0, 0); __builtin_amdgcn_s_setprio(0); } while (0)
; #define PG8_WAIT_V(n) asm volatile("s_waitcnt vmcnt(" #n ")" ::: "memory")
; #define PG8_WAIT_L(n) asm volatile("s_waitcnt lgkmcnt(" #n ")" ::: "memory")
; #define PG8_BAR __builtin_amdgcn_s_barrier()
; #define PG8_SCHED __builtin_amdgcn_sched_barrier(0)
; template <class Epi, class Sched, bool ALIGN_EPI = false, bool SP2 = false>
; __device__ __forceinline__ void gemm_phase(PG8_LAS unsigned char* lds, const Gemm g, const Sched& S, const Epi& E) {
;     ...
;             PG8_LDA(At, 1, 1); PG8_STAGE(PG8_SB(1, 0), b3, voffB); PG8_STAGE(PG8_SB(1, 1), b3 + hstepB, voffB); PG8_STAGE(PG8_SA(1, 0), a3, voffA);
;             PG8_WAIT_V(8); PG8_WAIT_L(0); PG8_BAR; PG8_MMA(1, 0, At, B0); PG8_MMA(1, 1, At, B1); PG8_BAR; PG8_SCHED;
	s_add_u32 s42, s40, 0x8000
	s_addc_u32 s43, s41, 0
	s_add_i32 s63, s63, s16
	v_lshl_add_u64 v[214:215], s[42:43], 0, v[140:141]
	s_mov_b32 m0, s63
	ds_read_b128 v[182:185], v168 offset:49152
	ds_read_b128 v[186:189], v168 offset:50176
	ds_read_b128 v[190:193], v168 offset:51200
	ds_read_b128 v[194:197], v168 offset:52224
	ds_read_b128 v[198:201], v168 offset:53248
	ds_read_b128 v[202:205], v168 offset:54272
	ds_read_b128 v[206:209], v168 offset:55296
	ds_read_b128 v[210:213], v168 offset:56320
	global_load_lds_dwordx4 v[214:215], off
	s_add_i32 m0, s63, 0x2000
	s_add_u32 s40, s40, 0xc000
	v_lshl_add_u64 v[214:215], s[42:43], 0, v[136:137]
	s_addc_u32 s41, s41, 0
	s_add_i32 s42, s66, s16
	global_load_lds_dwordx4 v[214:215], off
	v_lshl_add_u64 v[214:215], s[40:41], 0, v[140:141]
	s_mov_b32 m0, s42
	s_nop 0
	global_load_lds_dwordx4 v[214:215], off
	v_lshl_add_u64 v[214:215], s[40:41], 0, v[136:137]
	s_add_i32 m0, s42, 0x2000
	s_nop 0
	global_load_lds_dwordx4 v[214:215], off
	v_lshl_add_u64 v[214:215], s[38:39], 0, v[142:143]
	s_mov_b32 m0, s25
	s_nop 0
	global_load_lds_dwordx4 v[214:215], off
	v_lshl_add_u64 v[214:215], s[38:39], 0, v[138:139]
	s_mov_b32 m0, s26
	s_nop 0
	global_load_lds_dwordx4 v[214:215], off
	s_waitcnt vmcnt(8)
	s_waitcnt lgkmcnt(0)
	s_barrier
	s_setprio 1
	s_waitcnt lgkmcnt(0)
	v_mfma_f32_16x16x32_bf16 v[60:63], v[128:131], v[182:185], v[60:63]
	v_mfma_f32_16x16x32_bf16 v[60:63], v[132:135], v[186:189], v[60:63]
	v_mfma_f32_16x16x32_bf16 v[52:55], v[152:155], v[182:185], v[52:55]
	v_mfma_f32_16x16x32_bf16 v[52:55], v[156:159], v[186:189], v[52:55]
	v_mfma_f32_16x16x32_bf16 v[44:47], v[128:131], v[190:193], v[44:47]
	v_mfma_f32_16x16x32_bf16 v[44:47], v[132:135], v[194:197], v[44:47]
	v_mfma_f32_16x16x32_bf16 v[36:39], v[152:155], v[190:193], v[36:39]
	v_mfma_f32_16x16x32_bf16 v[36:39], v[156:159], v[194:197], v[36:39]
	v_mfma_f32_16x16x32_bf16 v[28:31], v[128:131], v[198:201], v[28:31]
	v_mfma_f32_16x16x32_bf16 v[28:31], v[132:135], v[202:205], v[28:31]
	v_mfma_f32_16x16x32_bf16 v[20:23], v[152:155], v[198:201], v[20:23]
	v_mfma_f32_16x16x32_bf16 v[20:23], v[156:159], v[202:205], v[20:23]
	v_mfma_f32_16x16x32_bf16 v[12:15], v[128:131], v[206:209], v[12:15]
	v_mfma_f32_16x16x32_bf16 v[12:15], v[132:135], v[210:213], v[12:15]
	v_mfma_f32_16x16x32_bf16 v[4:7], v[152:155], v[206:209], v[4:7]
	v_mfma_f32_16x16x32_bf16 v[4:7], v[156:159], v[210:213], v[4:7]
	s_setprio 0
	s_setprio 1
	v_mfma_f32_16x16x32_bf16 v[56:59], v[160:163], v[182:185], v[56:59]
	v_mfma_f32_16x16x32_bf16 v[56:59], v[170:173], v[186:189], v[56:59]
	v_mfma_f32_16x16x32_bf16 v[48:51], v[174:177], v[182:185], v[48:51]
	v_mfma_f32_16x16x32_bf16 v[48:51], v[178:181], v[186:189], v[48:51]
	v_mfma_f32_16x16x32_bf16 v[40:43], v[160:163], v[190:193], v[40:43]
	v_mfma_f32_16x16x32_bf16 v[40:43], v[170:173], v[194:197], v[40:43]
	v_mfma_f32_16x16x32_bf16 v[32:35], v[174:177], v[190:193], v[32:35]
	v_mfma_f32_16x16x32_bf16 v[32:35], v[178:181], v[194:197], v[32:35]
	v_mfma_f32_16x16x32_bf16 v[24:27], v[160:163], v[198:201], v[24:27]
	v_mfma_f32_16x16x32_bf16 v[24:27], v[170:173], v[202:205], v[24:27]
	v_mfma_f32_16x16x32_bf16 v[16:19], v[174:177], v[198:201], v[16:19]
	v_mfma_f32_16x16x32_bf16 v[16:19], v[178:181], v[202:205], v[16:19]
	v_mfma_f32_16x16x32_bf16 v[8:11], v[160:163], v[206:209], v[8:11]
	v_mfma_f32_16x16x32_bf16 v[8:11], v[170:173], v[210:213], v[8:11]
	v_mfma_f32_16x16x32_bf16 v[0:3], v[174:177], v[206:209], v[0:3]
	v_mfma_f32_16x16x32_bf16 v[0:3], v[178:181], v[210:213], v[0:3]
	s_setprio 0
	s_barrier
	s_add_i32 s62, s62, 2
	s_add_u32 s36, s36, 0x10000
	s_addc_u32 s37, s37, 0
	s_add_u32 s44, s44, 0x10000
	s_addc_u32 s45, s45, 0
	s_cmp_gt_u32 s62, 29
	s_cbranch_scc0 .LBB0_263
	s_and_b64 vcc, exec, s[8:9]
	s_cbranch_vccz .LBB0_266
	s_barrier
